# cv26 + P2 scan loop: unit-start wait vmcnt(0)->vmcnt(4) (only previous unit's 4 stage-D stores in flight) + stage-D LDS read ladder de-serialised
# baseline (speedup 1.0000x reference)
.LBB0_635:
	s_or_b64 exec, exec, s[12:13]
	s_lshl_b32 s12, s36, 6
	s_lshl_b32 s13, s38, 11
	s_add_i32 s36, s12, s13
	s_waitcnt lgkmcnt(0)
	s_waitcnt lgkmcnt(0)
	s_barrier
	ds_read_b128 v[60:63], v134 offset:53248
	ds_read_b128 v[142:145], v135
	ds_read_b128 v[146:149], v137 offset:53248
	ds_read_b128 v[150:153], v138
	v_add_u32_e32 v68, s36, v110
	s_lshl_b64 s[12:13], s[20:21], 1
	v_ashrrev_i32_e32 v69, 31, v68
	v_lshl_add_u64 v[64:65], v[94:95], 0, s[12:13]
	v_lshlrev_b64 v[68:69], 12, v[68:69]
	v_lshl_add_u64 v[70:71], v[64:65], 0, v[68:69]
	s_waitcnt lgkmcnt(3)
	global_store_dwordx4 v[70:71], v[60:63], off
	v_lshl_add_u64 v[66:67], v[96:97], 0, s[12:13]
	v_lshl_add_u64 v[68:69], v[66:67], 0, v[68:69]
	v_readlane_b32 s12, v252, 18
	v_mov_b64_e32 v[74:75], v[38:39]
	s_waitcnt lgkmcnt(2)
	global_store_dwordx4 v[68:69], v[142:145], off
	v_add_u32_e32 v68, s36, v136
	v_ashrrev_i32_e32 v69, 31, v68
	v_lshlrev_b64 v[68:69], 12, v[68:69]
	v_lshl_add_u64 v[64:65], v[64:65], 0, v[68:69]
	s_waitcnt lgkmcnt(1)
	global_store_dwordx4 v[64:65], v[146:149], off
	v_lshl_add_u64 v[64:65], v[66:67], 0, v[68:69]
	v_mov_b64_e32 v[70:71], v[46:47]
	v_mov_b64_e32 v[78:79], v[50:51]
	v_mov_b64_e32 v[82:83], v[42:43]
	s_waitcnt lgkmcnt(0)
	global_store_dwordx4 v[64:65], v[150:153], off
	v_mov_b64_e32 v[66:67], v[54:55]
	v_mov_b64_e32 v[86:87], v[32:33]
	v_mov_b64_e32 v[62:63], v[58:59]
	v_mov_b64_e32 v[90:91], v[28:29]
	s_add_i32 s26, s26, s12
	s_and_b64 vcc, exec, s[8:9]
	s_mov_b32 s38, s14
	v_mov_b32_e32 v101, v102
	v_mov_b32_e32 v15, v99
	v_mov_b32_e32 v141, v103
	v_mov_b64_e32 v[60:61], v[56:57]
	v_mov_b64_e32 v[64:65], v[52:53]
	v_mov_b64_e32 v[68:69], v[44:45]
	v_mov_b64_e32 v[72:73], v[36:37]
	v_mov_b64_e32 v[76:77], v[48:49]
	v_mov_b64_e32 v[80:81], v[40:41]
	v_mov_b64_e32 v[84:85], v[30:31]
	v_mov_b64_e32 v[88:89], v[26:27]
	s_cbranch_vccnz .LBB0_658

.LBB0_643:
	s_or_b64 exec, exec, s[8:9]
	s_add_i32 s39, s39, s20
	s_load_dwordx4 s[72:75], s[0:1], 0x68
	s_load_dwordx2 s[8:9], s[0:1], 0x58
	v_or_b32_e32 v102, s39, v107
	v_ashrrev_i32_e32 v103, 31, v102
	v_lshl_add_u64 v[102:103], v[102:103], 0, s[4:5]
	v_lshlrev_b64 v[102:103], 2, v[102:103]
	s_waitcnt lgkmcnt(0)
	v_lshl_add_u64 v[104:105], s[74:75], 0, v[102:103]
	global_load_dword v144, v[104:105], off
	v_lshl_add_u64 v[104:105], s[8:9], 0, v[102:103]
	s_mov_b32 s8, 0xbfb8aa3b
	v_lshl_add_u64 v[142:143], s[72:73], 0, v[102:103]
	global_load_dword v102, v[104:105], off
	global_load_dword v99, v[142:143], off
	s_waitcnt lgkmcnt(0)
	v_readlane_b32 s74, v252, 47
	v_readlane_b32 s75, v252, 48
	s_barrier
	s_waitcnt vmcnt(2)
	v_mul_f32_e64 v103, |v144|, s8
	v_fma_f32 v104, |v144|, s8, -v103
	v_rndne_f32_e32 v105, v103
	s_mov_b32 s8, 0xb2a5705f
	v_fma_f32 v104, |v144|, s8, v104
	v_sub_f32_e32 v103, v103, v105
	v_add_f32_e32 v103, v103, v104
	v_cvt_i32_f32_e32 v105, v105
	v_exp_f32_e32 v103, v103
	s_mov_b32 s8, 0x42ce8ed0
	v_cmp_ngt_f32_e64 vcc, |v144|, s8
	s_mov_b32 s8, 0xc2b17218
	v_ldexp_f32 v103, v103, v105
	v_cndmask_b32_e32 v103, 0, v103, vcc
	v_cmp_nlt_f32_e64 vcc, |v144|, s8
	v_max_f32_e32 v104, v144, v144
	v_min_f32_e32 v154, 0, v104
	v_cndmask_b32_e32 v103, v211, v103, vcc
	v_add_f32_e32 v142, 1.0, v103
	v_add_f32_e32 v143, -1.0, v142
	v_frexp_mant_f32_e32 v144, v142
	v_cvt_f64_f32_e32 v[104:105], v142
	s_mov_b32 s8, 0x3f2aaaab
	v_sub_f32_e32 v145, v143, v142
	v_frexp_exp_i32_f64_e32 v104, v[104:105]
	v_cmp_gt_f32_e32 vcc, s8, v144
	v_sub_f32_e32 v143, v103, v143
	v_add_f32_e32 v105, 1.0, v145
	v_subbrev_co_u32_e32 v104, vcc, 0, v104, vcc
	v_add_f32_e32 v105, v143, v105
	v_sub_u32_e32 v143, 0, v104
	v_ldexp_f32 v142, v142, v143
	v_add_f32_e32 v144, -1.0, v142
	v_add_f32_e32 v145, 1.0, v142
	v_ldexp_f32 v105, v105, v143
	v_add_f32_e32 v143, 1.0, v144
	v_add_f32_e32 v146, -1.0, v145
	v_sub_f32_e32 v143, v142, v143
	v_sub_f32_e32 v142, v142, v146
	v_add_f32_e32 v146, v105, v143
	v_add_f32_e32 v105, v105, v142
	v_add_f32_e32 v148, v145, v105
	v_rcp_f32_e32 v149, v148
	v_add_f32_e32 v143, v144, v146
	v_sub_f32_e32 v144, v144, v143
	v_sub_f32_e32 v142, v145, v148
	v_mul_f32_e32 v151, v143, v149
	v_add_f32_e32 v150, v146, v144
	v_mul_f32_e32 v144, v148, v151
	v_add_f32_e32 v105, v105, v142
	v_fma_f32 v146, v151, v148, -v144
	v_fmac_f32_e32 v146, v151, v105
	v_add_f32_e32 v142, v144, v146
	v_sub_f32_e32 v145, v143, v142
	v_mov_b32_e32 v147, v142
	v_pk_add_f32 v[142:143], v[142:143], v[144:145] neg_lo:[0,1] neg_hi:[0,1]
	v_cvt_f32_i32_e32 v104, v104
	v_pk_add_f32 v[142:143], v[142:143], v[146:147] neg_lo:[0,1] neg_hi:[0,1]
	s_mov_b32 s8, 0x3f317218
	v_add_f32_e32 v143, v150, v143
	v_add_f32_e32 v142, v142, v143
	v_add_f32_e32 v143, v145, v142
	v_mul_f32_e32 v147, v149, v143
	v_mul_f32_e32 v144, v148, v147
	v_sub_f32_e32 v145, v145, v143
	v_add_f32_e32 v152, v151, v147
	v_fma_f32 v146, v147, v148, -v144
	v_add_f32_e32 v150, v142, v145
	v_sub_f32_e32 v142, v152, v151
	v_fmac_f32_e32 v146, v147, v105
	v_sub_f32_e32 v105, v147, v142
	v_add_f32_e32 v142, v144, v146
	v_sub_f32_e32 v145, v143, v142
	v_mov_b32_e32 v147, v142
	v_pk_add_f32 v[142:143], v[142:143], v[144:145] neg_lo:[0,1] neg_hi:[0,1]
	s_nop 0
	v_pk_add_f32 v[142:143], v[142:143], v[146:147] neg_lo:[0,1] neg_hi:[0,1]
	s_nop 0
	v_add_f32_e32 v143, v150, v143
	v_add_f32_e32 v142, v142, v143
	v_add_f32_e32 v142, v145, v142
	v_mul_f32_e32 v142, v149, v142
	v_add_f32_e32 v105, v105, v142
	v_add_f32_e32 v142, v152, v105
	v_mul_f32_e32 v144, v142, v142
	v_sub_f32_e32 v145, v142, v152
	v_fmamk_f32 v146, v144, 0x3e9b6dac, v207
	v_sub_f32_e32 v145, v105, v145
	v_mul_f32_e32 v105, v142, v144
	v_fmaak_f32 v183, v144, v146, 0x3f2aaada
	v_ldexp_f32 v147, v145, 1
	v_pk_mul_f32 v[144:145], v[104:105], v[182:183]
	v_ldexp_f32 v143, v142, 1
	v_fma_f32 v142, v104, s8, -v144
	v_fmac_f32_e32 v142, 0xb102e308, v104
	v_pk_add_f32 v[104:105], v[144:145], v[142:143]
	v_mov_b32_e32 v146, v144
	v_sub_f32_e32 v150, v105, v143
	v_pk_add_f32 v[148:149], v[104:105], v[144:145] neg_lo:[0,1] neg_hi:[0,1]
	v_sub_f32_e32 v144, v145, v150
	v_add_f32_e32 v147, v147, v144
	v_pk_add_f32 v[144:145], v[104:105], v[146:147]
	v_mov_b32_e32 v143, v104
	v_mov_b32_e32 v149, v145
	v_pk_add_f32 v[152:153], v[142:143], v[148:149] neg_lo:[0,1] neg_hi:[0,1]
	v_pk_add_f32 v[142:143], v[142:143], v[148:149]
	v_mov_b32_e32 v151, v104
	v_pk_add_f32 v[148:149], v[142:143], v[104:105] op_sel:[1,0] op_sel_hi:[0,1] neg_lo:[0,1] neg_hi:[0,1]
	v_mov_b32_e32 v150, v147
	v_mov_b32_e32 v146, v145
	v_mov_b32_e32 v147, v143
	v_pk_mov_b32 v[104:105], v[104:105], v[148:149] op_sel:[1,0]
	v_pk_add_f32 v[144:145], v[144:145], v[148:149] op_sel_hi:[1,0] neg_lo:[0,1] neg_hi:[0,1]
	v_pk_add_f32 v[104:105], v[146:147], v[104:105] neg_lo:[0,1] neg_hi:[0,1]
	v_mov_b32_e32 v144, v152
	v_pk_add_f32 v[104:105], v[150:151], v[104:105] neg_lo:[0,1] neg_hi:[0,1]
	v_mov_b32_e32 v153, v143
	v_pk_add_f32 v[144:145], v[144:145], v[104:105]
	s_mov_b32 s8, 0x7f800000
	v_pk_add_f32 v[146:147], v[144:145], v[144:145] op_sel:[0,1] op_sel_hi:[1,0]
	v_cmp_neq_f32_e32 vcc, s8, v103
	v_pk_add_f32 v[142:143], v[142:143], v[146:147] op_sel:[1,0] op_sel_hi:[0,1]
	v_mov_b32_e32 v145, v142
	v_mov_b32_e32 v105, v146
	v_pk_add_f32 v[146:147], v[144:145], v[152:153] neg_lo:[0,1] neg_hi:[0,1]
	s_mov_b32 s8, 0x33800000
	v_sub_f32_e32 v143, v144, v146
	v_pk_add_f32 v[104:105], v[104:105], v[146:147] neg_lo:[0,1] neg_hi:[0,1]
	v_sub_f32_e32 v143, v152, v143
	v_add_f32_e32 v104, v104, v143
	v_add_f32_e32 v104, v104, v105
	v_add_f32_e32 v104, v142, v104
	v_cndmask_b32_e32 v104, v211, v104, vcc
	v_cmp_lt_f32_e64 vcc, |v103|, s8
	s_waitcnt vmcnt(0)
	s_mov_b64 s[8:9], 0
	s_nop 0
	v_cndmask_b32_e32 v103, v104, v103, vcc
	v_sub_f32_e32 v103, v154, v103
	v_mul_f32_e32 v103, 0x4138aa3b, v103
.LBB0_644:
	s_and_b64 vcc, exec, s[8:9]
	s_cbranch_vccz .LBB0_646
	v_mov_b64_e32 v[26:27], v[88:89]
	v_mov_b64_e32 v[30:31], v[84:85]
	v_mov_b64_e32 v[40:41], v[80:81]
	v_mov_b64_e32 v[48:49], v[76:77]
	v_mov_b64_e32 v[36:37], v[72:73]
	v_mov_b64_e32 v[44:45], v[68:69]
	v_mov_b64_e32 v[52:53], v[64:65]
	v_mov_b64_e32 v[56:57], v[60:61]
	s_lshl_b32 s20, s38, 7
	v_mov_b64_e32 v[28:29], v[90:91]
	v_mov_b64_e32 v[32:33], v[86:87]
	v_mov_b64_e32 v[42:43], v[82:83]
	v_mov_b64_e32 v[50:51], v[78:79]
	v_mov_b64_e32 v[38:39], v[74:75]
	v_mov_b64_e32 v[46:47], v[70:71]
	v_mov_b64_e32 v[54:55], v[66:67]
	v_mov_b64_e32 v[58:59], v[62:63]
	v_mov_b32_e32 v103, v141
	s_waitcnt vmcnt(4)
	v_mov_b32_e32 v99, v15
	v_mov_b32_e32 v102, v101
	s_mov_b32 s14, s38
.LBB0_646:
	v_add_u32_e32 v15, 0, v109
	v_add_u32_e32 v15, 0x17000, v15
	s_waitcnt vmcnt(4)
	v_lshlrev_b32_e32 v62, 16, v2
	v_and_b32_e32 v63, 0xffff0000, v2
	ds_read_b128 v[70:73], v15
	ds_read_b128 v[82:85], v15 offset:16
	ds_read_b128 v[74:77], v15 offset:2048
	ds_read_b128 v[78:81], v15 offset:512
	ds_read_b128 v[86:89], v15 offset:1024
	ds_read_b128 v[142:145], v15 offset:1536
	ds_read_b128 v[146:149], v15 offset:2064
	v_lshlrev_b32_e32 v66, 16, v6
	v_and_b32_e32 v67, 0xffff0000, v6
	s_waitcnt lgkmcnt(4)
	v_pk_fma_f32 v[62:63], v[70:71], v[62:63], v[74:75]
	v_lshlrev_b32_e32 v64, 16, v10
	v_and_b32_e32 v65, 0xffff0000, v10
	s_waitcnt lgkmcnt(3)
	v_pk_fma_f32 v[62:63], v[78:79], v[66:67], v[62:63]
	v_lshlrev_b32_e32 v60, 16, v18
	v_and_b32_e32 v61, 0xffff0000, v18
	s_waitcnt lgkmcnt(2)
	v_pk_fma_f32 v[62:63], v[86:87], v[64:65], v[62:63]
	ds_read_b128 v[150:153], v15 offset:528
	ds_read_b128 v[154:157], v15 offset:1040
	s_waitcnt lgkmcnt(3)
	v_pk_fma_f32 v[162:163], v[142:143], v[60:61], v[62:63]
	v_pk_fma_f32 v[62:63], v[70:71], v[66:67], v[74:75]
	v_lshlrev_b32_e32 v70, 16, v3
	v_and_b32_e32 v71, 0xffff0000, v3
	v_pk_fma_f32 v[62:63], v[78:79], v[64:65], v[62:63]
	v_lshlrev_b32_e32 v74, 16, v7
	v_and_b32_e32 v75, 0xffff0000, v7
	v_pk_fma_f32 v[70:71], v[72:73], v[70:71], v[76:77]
	v_lshlrev_b32_e32 v68, 16, v22
	v_and_b32_e32 v69, 0xffff0000, v22
	v_pk_fma_f32 v[62:63], v[86:87], v[60:61], v[62:63]
	v_lshlrev_b32_e32 v66, 16, v11
	v_and_b32_e32 v67, 0xffff0000, v11
	v_pk_fma_f32 v[70:71], v[80:81], v[74:75], v[70:71]
	v_pk_fma_f32 v[72:73], v[72:73], v[74:75], v[76:77]
	v_pk_fma_f32 v[86:87], v[142:143], v[68:69], v[62:63]
	v_lshlrev_b32_e32 v62, 16, v19
	v_and_b32_e32 v63, 0xffff0000, v19
	v_pk_fma_f32 v[70:71], v[88:89], v[66:67], v[70:71]
	v_pk_fma_f32 v[72:73], v[80:81], v[66:67], v[72:73]
	ds_read_b128 v[158:161], v15 offset:1552
	v_pk_fma_f32 v[164:165], v[144:145], v[62:63], v[70:71]
	v_lshlrev_b32_e32 v70, 16, v23
	v_and_b32_e32 v71, 0xffff0000, v23
	v_pk_fma_f32 v[72:73], v[88:89], v[62:63], v[72:73]
	v_lshlrev_b32_e32 v74, 16, v8
	v_pk_fma_f32 v[88:89], v[144:145], v[70:71], v[72:73]
	v_lshlrev_b32_e32 v72, 16, v4
	v_and_b32_e32 v73, 0xffff0000, v4
	v_and_b32_e32 v75, 0xffff0000, v8
	s_waitcnt lgkmcnt(3)
	v_pk_fma_f32 v[72:73], v[82:83], v[72:73], v[146:147]
	v_lshlrev_b32_e32 v80, 16, v12
	v_and_b32_e32 v81, 0xffff0000, v12
	s_waitcnt lgkmcnt(2)
	v_pk_fma_f32 v[72:73], v[150:151], v[74:75], v[72:73]
	v_pk_fma_f32 v[74:75], v[82:83], v[74:75], v[146:147]
	v_lshlrev_b32_e32 v76, 16, v20
	v_and_b32_e32 v77, 0xffff0000, v20
	s_waitcnt lgkmcnt(1)
	v_pk_fma_f32 v[72:73], v[154:155], v[80:81], v[72:73]
	v_pk_fma_f32 v[74:75], v[150:151], v[80:81], v[74:75]
	s_waitcnt lgkmcnt(0)
	v_pk_fma_f32 v[142:143], v[158:159], v[76:77], v[72:73]
	v_lshlrev_b32_e32 v72, 16, v24
	v_and_b32_e32 v73, 0xffff0000, v24
	v_pk_fma_f32 v[74:75], v[154:155], v[76:77], v[74:75]
	v_lshlrev_b32_e32 v90, 16, v9
	v_pk_fma_f32 v[146:147], v[158:159], v[72:73], v[74:75]
	v_lshlrev_b32_e32 v74, 16, v5
	v_and_b32_e32 v75, 0xffff0000, v5
	v_and_b32_e32 v91, 0xffff0000, v9
	v_pk_fma_f32 v[74:75], v[84:85], v[74:75], v[148:149]
	v_lshlrev_b32_e32 v82, 16, v13
	v_and_b32_e32 v83, 0xffff0000, v13
	v_pk_fma_f32 v[74:75], v[152:153], v[90:91], v[74:75]
	v_pk_fma_f32 v[84:85], v[84:85], v[90:91], v[148:149]
	s_ashr_i32 s8, s27, 4
	v_lshlrev_b32_e32 v78, 16, v21
	v_and_b32_e32 v79, 0xffff0000, v21
	v_pk_fma_f32 v[74:75], v[156:157], v[82:83], v[74:75]
	v_pk_fma_f32 v[84:85], v[152:153], v[82:83], v[84:85]
	s_lshr_b32 s9, s8, 27
	v_pk_fma_f32 v[144:145], v[160:161], v[78:79], v[74:75]
	v_lshlrev_b32_e32 v74, 16, v25
	v_and_b32_e32 v75, 0xffff0000, v25
	v_pk_fma_f32 v[84:85], v[156:157], v[78:79], v[84:85]
	v_bfe_u32 v91, v164, 16, 1
	v_bfe_u32 v104, v162, 16, 1
	v_bfe_u32 v105, v142, 16, 1
	s_add_i32 s9, s8, s9
	v_pk_fma_f32 v[148:149], v[160:161], v[74:75], v[84:85]
	v_bfe_u32 v84, v165, 16, 1
	v_bfe_u32 v85, v143, 16, 1
	v_bfe_u32 v90, v163, 16, 1
	v_bfe_u32 v101, v144, 16, 1
	v_add3_u32 v91, v164, v91, s69
	v_add3_u32 v105, v142, v105, s69
	v_add3_u32 v104, v162, v104, s69
	s_ashr_i32 s38, s9, 5
	s_andn2_b32 s9, s9, 31
	v_bfe_u32 v15, v145, 16, 1
	v_add3_u32 v84, v165, v84, s69
	v_add3_u32 v90, v163, v90, s69
	v_add3_u32 v85, v143, v85, s69
	v_add3_u32 v101, v144, v101, s69
	v_lshrrev_b32_e32 v91, 16, v91
	v_lshrrev_b32_e32 v104, 16, v104
	v_lshrrev_b32_e32 v105, 16, v105
	s_sub_i32 s36, s8, s9
	ds_write_b128 v111, v[162:165] offset:20480
	ds_write_b128 v111, v[142:145] offset:20496
	ds_write_b128 v112, v[86:89] offset:20480
	ds_write_b128 v112, v[146:149] offset:20496
	v_add3_u32 v15, v145, v15, s69
	v_lshrrev_b32_e32 v101, 16, v101
	v_and_or_b32 v143, v84, s7, v91
	v_and_or_b32 v144, v85, s7, v105
	v_and_or_b32 v142, v90, s7, v104
	v_bfe_u32 v84, v89, 16, 1
	v_bfe_u32 v85, v147, 16, 1
	v_bfe_u32 v90, v87, 16, 1
	v_and_or_b32 v145, v15, s7, v101
	v_add3_u32 v84, v89, v84, s69
	v_add3_u32 v89, v87, v90, s69
	v_add3_u32 v90, v147, v85, s69
	v_bfe_u32 v85, v88, 16, 1
	v_bfe_u32 v87, v148, 16, 1
	v_bfe_u32 v91, v86, 16, 1
	v_bfe_u32 v101, v146, 16, 1
	s_cmp_eq_u32 s36, 31
	v_bfe_u32 v15, v149, 16, 1
	v_add3_u32 v87, v148, v87, s69
	v_add3_u32 v85, v88, v85, s69
	v_add3_u32 v88, v146, v101, s69
	v_add3_u32 v86, v86, v91, s69
	s_cselect_b64 s[8:9], -1, 0
	v_readfirstlane_b32 s37, v189
	v_add3_u32 v15, v149, v15, s69
	v_lshrrev_b32_e32 v85, 16, v85
	v_lshrrev_b32_e32 v87, 16, v87
	v_lshrrev_b32_e32 v91, 16, v86
	v_lshrrev_b32_e32 v86, 16, v88
	s_and_b64 s[12:13], s[50:51], s[8:9]
	v_and_or_b32 v87, v15, s7, v87
	v_and_or_b32 v85, v84, s7, v85
	v_and_or_b32 v86, v90, s7, v86
	v_and_or_b32 v84, v89, s7, v91
	ds_write_b128 v113, v[142:145]
	ds_write_b128 v114, v[84:87]
	s_and_saveexec_b64 s[8:9], s[12:13]
	s_cbranch_execz .LBB0_648
	s_load_dwordx2 s[12:13], s[0:1], 0xb8
	s_add_i32 s39, s38, s6
	s_lshl_b64 s[60:61], s[20:21], 2
	v_mov_b32_e32 v101, v35
	s_waitcnt lgkmcnt(0)
	s_add_u32 s12, s12, s60
	s_addc_u32 s13, s13, s61
	v_lshl_add_u64 v[84:85], s[12:13], 0, v[100:101]
	s_mov_b64 s[12:13], 0x4420000
	v_lshl_add_u64 v[84:85], v[84:85], 0, s[12:13]
	v_mad_i64_i32 v[84:85], s[12:13], s39, v212, v[84:85]
	global_store_dwordx4 v[84:85], v[64:67], off
	global_store_dwordx4 v[84:85], v[80:83], off offset:16
	s_nop 0
	v_add_co_u32_e32 v64, vcc, s15, v84
	s_nop 1
	v_addc_co_u32_e32 v65, vcc, 0, v85, vcc
	global_store_dwordx4 v[64:65], v[60:63], off
	global_store_dwordx4 v[64:65], v[76:79], off offset:16
	s_nop 0
	v_add_co_u32_e32 v60, vcc, 0x4000, v84
	s_nop 1
	v_addc_co_u32_e32 v61, vcc, 0, v85, vcc
	global_store_dwordx4 v[60:61], v[68:71], off
	global_store_dwordx4 v[60:61], v[72:75], off offset:16
